# ssd1 (phase 9) staging: 12 serialized loads per half batched ahead of the barrier, LDS writes behind counted vmcnt
# speedup vs baseline: 1.0092x; 1.0023x over previous
.LBB0_169:
	v_mov_b32_e32 v0, v179
	s_xor_b64 s[4:5], s[6:7], -1
	s_or_b32 s6, s1, s11
	v_mov_b32_e32 v131, s10
	v_and_b32_e32 v134, 0x7f, v0
	v_or_b32_e32 v130, s6, v134
	v_ashrrev_i32_e32 v0, 1, v0
	v_lshlrev_b64 v[130:131], 13, v[130:131]
	v_and_b32_e32 v132, 0xffffffc0, v0
	v_lshl_add_u64 v[130:131], s[2:3], 0, v[130:131]
	v_ashrrev_i32_e32 v133, 31, v132
	v_lshl_add_u64 v[130:131], v[132:133], 1, v[130:131]
	v_mul_lo_u32 v0, v132, s12
	v_lshlrev_b32_e32 v136, 1, v134
	global_load_dwordx4 v[204:207], v[130:131], off
	global_load_dwordx4 v[208:211], v[130:131], off offset:16
	global_load_dwordx4 v[212:215], v[130:131], off offset:32
	global_load_dwordx4 v[222:225], v[130:131], off offset:48
	global_load_dwordx4 v[226:229], v[130:131], off offset:64
	global_load_dwordx4 v[230:233], v[130:131], off offset:80
	global_load_dwordx4 v[240:243], v[130:131], off offset:96
	global_load_dwordx4 v[244:247], v[130:131], off offset:112
	v_add3_u32 v137, 32, v0, v136
	v_add3_u32 v0, 32, v136, v0
	v_mov_b32_e32 v188, v185
	v_mov_b32_e32 v189, v184
	v_mov_b32_e32 v133, s10
	v_or_b32_e32 v132, s6, v148
	v_lshlrev_b64 v[132:133], 13, v[132:133]
	v_lshl_add_u64 v[132:133], s[38:39], 0, v[132:133]
	v_lshl_add_u64 v[132:133], v[132:133], 0, s[50:51]
	v_lshl_add_u64 v[132:133], v[150:151], 1, v[132:133]
	s_mov_b64 s[6:7], 0x1000
	v_lshl_add_u64 v[134:135], v[132:133], 0, s[6:7]
	v_add_co_u32_e32 v132, vcc, s37, v132
	s_nop 1
	v_addc_co_u32_e32 v133, vcc, 0, v133, vcc
	global_load_dwordx4 v[138:141], v[132:133], off
	global_load_dwordx4 v[190:193], v[134:135], off offset:16
	global_load_dwordx4 v[200:203], v[134:135], off offset:32
	s_waitcnt lgkmcnt(0)
	s_barrier
	s_waitcnt vmcnt(10)
	ds_write_b16 v137, v204
	ds_write_b16_d16_hi v0, v204 offset:272
	ds_write_b16 v137, v205 offset:544
	ds_write_b16_d16_hi v0, v205 offset:816
	ds_write_b16 v137, v206 offset:1088
	ds_write_b16_d16_hi v0, v206 offset:1360
	ds_write_b16 v137, v207 offset:1632
	ds_write_b16_d16_hi v0, v207 offset:1904
	global_load_dwordx4 v[204:207], v[134:135], off offset:48
	s_waitcnt vmcnt(10)
	ds_write_b16 v137, v208 offset:2176
	ds_write_b16_d16_hi v0, v208 offset:2448
	ds_write_b16 v137, v209 offset:2720
	ds_write_b16_d16_hi v0, v209 offset:2992
	ds_write_b16 v137, v210 offset:3264
	ds_write_b16_d16_hi v0, v210 offset:3536
	ds_write_b16 v137, v211 offset:3808
	ds_write_b16_d16_hi v0, v211 offset:4080
	s_waitcnt vmcnt(9)
	ds_write_b16 v137, v212 offset:4352
	ds_write_b16_d16_hi v0, v212 offset:4624
	ds_write_b16 v137, v213 offset:4896
	ds_write_b16_d16_hi v0, v213 offset:5168
	ds_write_b16 v137, v214 offset:5440
	ds_write_b16_d16_hi v0, v214 offset:5712
	ds_write_b16 v137, v215 offset:5984
	ds_write_b16_d16_hi v0, v215 offset:6256
	s_waitcnt vmcnt(8)
	ds_write_b16 v137, v222 offset:6528
	ds_write_b16_d16_hi v0, v222 offset:6800
	ds_write_b16 v137, v223 offset:7072
	ds_write_b16_d16_hi v0, v223 offset:7344
	ds_write_b16 v137, v224 offset:7616
	ds_write_b16_d16_hi v0, v224 offset:7888
	ds_write_b16 v137, v225 offset:8160
	ds_write_b16_d16_hi v0, v225 offset:8432
	s_waitcnt vmcnt(7)
	ds_write_b16 v137, v226 offset:8704
	ds_write_b16_d16_hi v0, v226 offset:8976
	ds_write_b16 v137, v227 offset:9248
	ds_write_b16_d16_hi v0, v227 offset:9520
	ds_write_b16 v137, v228 offset:9792
	ds_write_b16_d16_hi v0, v228 offset:10064
	ds_write_b16 v137, v229 offset:10336
	ds_write_b16_d16_hi v0, v229 offset:10608
	s_waitcnt vmcnt(6)
	ds_write_b16 v137, v230 offset:10880
	ds_write_b16_d16_hi v0, v230 offset:11152
	ds_write_b16 v137, v231 offset:11424
	ds_write_b16_d16_hi v0, v231 offset:11696
	ds_write_b16 v137, v232 offset:11968
	ds_write_b16_d16_hi v0, v232 offset:12240
	ds_write_b16 v137, v233 offset:12512
	ds_write_b16_d16_hi v0, v233 offset:12784
	s_waitcnt vmcnt(5)
	ds_write_b16 v137, v240 offset:13056
	ds_write_b16_d16_hi v0, v240 offset:13328
	ds_write_b16 v137, v241 offset:13600
	ds_write_b16_d16_hi v0, v241 offset:13872
	ds_write_b16 v137, v242 offset:14144
	ds_write_b16_d16_hi v0, v242 offset:14416
	ds_write_b16 v137, v243 offset:14688
	ds_write_b16_d16_hi v0, v243 offset:14960
	s_waitcnt vmcnt(4)
	ds_write_b16 v137, v244 offset:15232
	ds_write_b16_d16_hi v0, v244 offset:15504
	ds_write_b16 v137, v245 offset:15776
	ds_write_b16_d16_hi v0, v245 offset:16048
	ds_write_b16 v137, v246 offset:16320
	ds_write_b16_d16_hi v0, v246 offset:16592
	ds_write_b16 v137, v247 offset:16864
	ds_write_b16_d16_hi v0, v247 offset:17136
	s_waitcnt vmcnt(3)
	ds_write_b16 v165, v138
	ds_write_b16_d16_hi v166, v138 offset:272
	ds_write_b16 v165, v139 offset:544
	ds_write_b16_d16_hi v167, v139 offset:272
	ds_write_b16 v165, v140 offset:1088
	ds_write_b16_d16_hi v168, v140 offset:272
	ds_write_b16 v165, v141 offset:1632
	ds_write_b16_d16_hi v169, v141 offset:272
	s_waitcnt vmcnt(2)
	ds_write_b16 v165, v190 offset:2176
	ds_write_b16_d16_hi v170, v190 offset:272
	ds_write_b16 v165, v191 offset:2720
	ds_write_b16_d16_hi v171, v191 offset:272
	ds_write_b16 v165, v192 offset:3264
	ds_write_b16_d16_hi v172, v192 offset:272
	ds_write_b16 v165, v193 offset:3808
	ds_write_b16_d16_hi v173, v193 offset:272
	s_waitcnt vmcnt(1)
	ds_write_b16 v165, v200 offset:4352
	ds_write_b16_d16_hi v174, v200 offset:272
	ds_write_b16 v165, v201 offset:4896
	ds_write_b16_d16_hi v175, v201 offset:272
	ds_write_b16 v165, v202 offset:5440
	ds_write_b16_d16_hi v176, v202 offset:272
	ds_write_b16 v165, v203 offset:5984
	ds_write_b16_d16_hi v177, v203 offset:272
	s_waitcnt vmcnt(0)
	ds_write_b16 v165, v204 offset:6528
	ds_write_b16_d16_hi v180, v204 offset:272
	ds_write_b16 v165, v205 offset:7072
	ds_write_b16_d16_hi v181, v205 offset:272
	ds_write_b16 v165, v206 offset:7616
	ds_write_b16_d16_hi v182, v206 offset:272
	ds_write_b16 v165, v207 offset:8160
	ds_write_b16_d16_hi v183, v207 offset:272
	v_lshl_add_u32 v0, s11, 2, v186
	s_mov_b32 s6, 8
	s_waitcnt lgkmcnt(0)
	s_barrier
